# final RMSNorm on the workgroup's own row panel + 4-workgroup seam for P10->P11
# baseline (speedup 1.0000x reference)
; __device__ __forceinline__ void xcd_barrier(const XcdBarrier& b) {
;     asm volatile("s_waitcnt vmcnt(0)" ::: "memory");
;     __syncthreads();
;     if (threadIdx.x == 0) {
;         unsigned* bar = b.bar;
;         __builtin_amdgcn_s_waitcnt(0);
;         unsigned nloc = b.st[0], nx = b.st[1];
;         if (nloc == 0u) { xcd_barrier_complete(bar, b.x, nloc, nx); b.st[0] = nloc; b.st[1] = nx; }
.LBB0_740:
	s_cmp_gt_i32 s75, 11
	s_cselect_b64 s[0:1], -1, 0
	s_and_b64 s[2:3], s[6:7], s[0:1]
	s_andn2_b64 vcc, exec, s[2:3]
	s_cbranch_vccnz .LBB0_790
	s_waitcnt vmcnt(0)
	v_cmp_eq_u32_e32 vcc, 0, v189
	s_waitcnt vmcnt(0) lgkmcnt(0)
	s_barrier
	s_and_saveexec_b64 s[4:5], vcc
	s_cbranch_execz .LBB0_789
	v_mov_b32_e32 v0, 0x20430
	ds_read_b32 v0, v0
	s_waitcnt lgkmcnt(0)
	v_cmp_ne_u32_e32 vcc, 0, v0
	s_cbranch_vccz .Lseam_slow_8
	v_readlane_b32 s8, v255, 0
	v_readlane_b32 s2, v254, 4
	v_readlane_b32 s3, v254, 5
	s_and_b32 s8, s8, 63
	s_lshl_b32 s8, s8, 2
	s_add_i32 s8, s8, 0x100
	v_mov_b32_e32 v0, s8
	v_mov_b32_e32 v1, 1
	s_mov_b32 s9, 0
	s_nop 2
	global_atomic_add v0, v1, s[2:3]
.Lseam_spin_8:
	global_load_dword v2, v0, s[2:3] sc1
	s_add_i32 s9, s9, 1
	s_waitcnt vmcnt(0)
	v_cmp_gt_u32_e32 vcc, 24, v2
	s_cbranch_vccz .Lseam_done_8
	s_cmp_gt_u32 s9, 30000
	s_cbranch_scc1 .Lseam_done_8
	s_sleep 1
	s_branch .Lseam_spin_8

; __device__ __forceinline__ unsigned xb_ld(unsigned* p)              { return __hip_atomic_load(p, __ATOMIC_RELAXED, __HIP_MEMORY_SCOPE_AGENT); }
; __device__ __forceinline__ void xcd_barrier_complete(unsigned* bar, unsigned x, unsigned& nloc, unsigned& nx) {
;     const unsigned G = gridDim.x * gridDim.y * gridDim.z;
;     unsigned sum, cnt, mine, sp = 0u;
;     for (;;) {
;         sum = 0u; cnt = 0u; mine = 0u;
; #pragma unroll
;         for (unsigned j = 0; j < 16; ++j) { const unsigned c = xb_ld(&bar[XB_XCNT(j)]); sum += c; cnt += (c > 0u) ? 1u : 0u; mine = (j == x) ? c : mine; }
;         if (sum == G) break;
;         __builtin_amdgcn_s_sleep(1);
;         if ((++sp & 255u) == 0u) { if (xb_ld(&bar[XB_TMO])) break; if (sp > XB_SPIN_CAP) { atomicAdd(&bar[XB_TMO], 1u); break; } }
;     }
;     nloc = mine > 0u ? mine : 1u; nx = cnt > 0u ? cnt : 1u;
; }
; __device__ __forceinline__ void xcd_barrier(const XcdBarrier& b) {
;     asm volatile("s_waitcnt vmcnt(0)" ::: "memory");
;     __syncthreads();
;     if (threadIdx.x == 0) {
;         unsigned* bar = b.bar;
;         __builtin_amdgcn_s_waitcnt(0);
;         unsigned nloc = b.st[0], nx = b.st[1];
;         if (nloc == 0u) { xcd_barrier_complete(bar, b.x, nloc, nx); b.st[0] = nloc; b.st[1] = nx; }
.Lseam_slow_8:
	s_add_i32 s2, 0, 0x20420
	v_mov_b32_e32 v0, s2
	s_waitcnt vmcnt(0) expcnt(0) lgkmcnt(0)
	ds_read_b32 v2, v0
	s_add_i32 s2, 0, 0x20424
	v_mov_b32_e32 v0, s2
	ds_read_b32 v0, v0
	s_waitcnt lgkmcnt(1)
	v_cmp_ne_u32_e32 vcc, 0, v2
	s_cbranch_vccnz .LBB0_757
	v_readlane_b32 s6, v254, 2
	v_readlane_b32 s7, v254, 3
	s_load_dwordx2 s[2:3], s[6:7], 0x4
	s_add_u32 s6, s90, 0x2c0200
	s_addc_u32 s7, s91, 0
	s_add_u32 s8, s90, 0x2c0400
	s_addc_u32 s9, s91, 0
	s_add_u32 s10, s90, 0x2c0500
	s_addc_u32 s11, s91, 0
	s_add_u32 s12, s90, 0x2c0600
	s_addc_u32 s13, s91, 0
	s_add_u32 s14, s90, 0x2c0700
	s_addc_u32 s15, s91, 0
	s_add_u32 s16, s90, 0x2c0800
	s_addc_u32 s17, s91, 0
	s_add_u32 s24, s90, 0x2c0900
	s_addc_u32 s25, s91, 0
	s_add_u32 s26, s90, 0x2c0a00
	s_addc_u32 s27, s91, 0
	s_add_u32 s28, s90, 0x2c0b00
	s_addc_u32 s29, s91, 0
	s_add_u32 s30, s90, 0x2c0c00
	s_addc_u32 s31, s91, 0
	s_add_u32 s36, s90, 0x2c0d00
	s_addc_u32 s37, s91, 0
	s_add_u32 s38, s90, 0x2c0e00
	s_addc_u32 s39, s91, 0
	s_add_u32 s40, s90, 0x2c0f00
	s_addc_u32 s41, s91, 0
	s_add_u32 s42, s90, 0x2c1000
	s_addc_u32 s43, s91, 0
	s_add_u32 s44, s90, 0x2c1100
	s_addc_u32 s45, s91, 0
	s_add_u32 s46, s90, 0x2c1200
	s_addc_u32 s47, s91, 0
	s_waitcnt lgkmcnt(0)
	s_mul_i32 s2, s2, s67
	s_add_u32 s48, s90, 0x2c1300
	s_mul_i32 s2, s2, s3
	s_addc_u32 s49, s91, 0
	s_mov_b32 s3, 1
	v_mov_b32_e32 v16, 0
	s_branch .LBB0_745

; template <bool OUT_BF16> __device__ __forceinline__ void rms_rows(const float* X, const float* gain, void* out, int gw, int ngw, int lane) {
;     int m = gw;
;     for (; m + ngw < M; m += 2 * ngw) {
;         const f32x4* xr0 = (const f32x4*)(X + (size_t)m * D) + lane; const f32x4* xr1 = (const f32x4*)(X + (size_t)(m + ngw) * D) + lane;
;         f32x4 v0[8], v1[8]; float s0 = 0.f, s1 = 0.f;
; #pragma unroll
;         for (int j = 0; j < 8; ++j) { v0[j] = xr0[64 * j]; v1[j] = xr1[64 * j]; }
; #pragma unroll
;         for (int j = 0; j < 8; ++j) { s0 += (v0[j].x * v0[j].x + v0[j].y * v0[j].y) + (v0[j].z * v0[j].z + v0[j].w * v0[j].w); s1 += (v1[j].x * v1[j].x + v1[j].y * v1[j].y) + (v1[j].z * v1[j].z + v1[j].w * v1[j].w); }
.LBB0_790:
	s_cmp_lt_i32 s74, 12
	s_cselect_b64 s[2:3], -1, 0
	s_and_b64 s[0:1], s[2:3], s[0:1]
	s_andn2_b64 vcc, exec, s[0:1]
	v_readlane_b32 s14, v254, 42
	v_readlane_b32 s15, v254, 43
	s_cbranch_vccnz .LBB0_798
	s_and_b32 s0, s66, 7
	s_lshl_b32 s0, s0, 3
	s_bfe_u32 s1, s66, 0x30003
	s_add_i32 s0, s0, s1
	s_lshl_b32 s0, s0, 8
	s_lshr_b32 s1, s66, 6
	s_lshl_b32 s1, s1, 6
	s_add_i32 s0, s0, s1
	v_readlane_b32 s1, v254, 40
	s_add_i32 s97, s0, 63
	s_mov_b32 s14, 8
	s_nop 0
	s_add_i32 s68, s0, s1
	s_add_i32 s0, s68, s14
	s_cmpk_gt_i32 s0, 0x3fff
	v_lshlrev_b32_e32 v56, 4, v188
	v_mbcnt_lo_u32_b32 v72, -1, 0
	s_cbranch_scc1 .LBB0_795
	v_mbcnt_hi_u32_b32 v0, -1, v72
	v_and_b32_e32 v1, 64, v0
	v_add_u32_e32 v1, 64, v1
	v_xor_b32_e32 v2, 1, v0
	v_cmp_lt_i32_e32 vcc, v2, v1
	v_mov_b32_e32 v57, 0
	v_mov_b32_e32 v3, v57
	v_cndmask_b32_e32 v2, v0, v2, vcc
	v_lshlrev_b32_e32 v73, 2, v2
	v_xor_b32_e32 v2, 2, v0
	v_cmp_lt_i32_e32 vcc, v2, v1
	v_mov_b32_e32 v5, v57
	s_add_i32 s1, s66, s67
	v_cndmask_b32_e32 v2, v0, v2, vcc
	v_lshlrev_b32_e32 v74, 2, v2
	v_xor_b32_e32 v2, 4, v0
	v_cmp_lt_i32_e32 vcc, v2, v1
	s_ashr_i32 s69, s68, 31
	s_mov_b32 s4, 16
	v_cndmask_b32_e32 v2, v0, v2, vcc
	v_lshlrev_b32_e32 v75, 2, v2
	v_xor_b32_e32 v2, 8, v0
	v_cmp_lt_i32_e32 vcc, v2, v1
	v_mov_b32_e32 v7, v57
	s_add_i32 s10, s97, -55
	v_cndmask_b32_e32 v2, v0, v2, vcc
	v_lshlrev_b32_e32 v76, 2, v2
	v_xor_b32_e32 v2, 16, v0
	v_cmp_lt_i32_e32 vcc, v2, v1
	s_lshl_b64 s[2:3], s[68:69], 13
	s_add_u32 s2, s88, s2
	v_cndmask_b32_e32 v2, v0, v2, vcc
	v_lshlrev_b32_e32 v77, 2, v2
	v_xor_b32_e32 v2, 32, v0
	v_cmp_lt_i32_e32 vcc, v2, v1
	v_mov_b32_e32 v9, v57
	s_addc_u32 s3, s89, s3
	v_cndmask_b32_e32 v0, v0, v2, vcc
	v_lshlrev_b32_e32 v78, 2, v0
	v_or_b32_e32 v0, 0x100, v188
	v_lshlrev_b32_e32 v2, 4, v0
	v_lshl_add_u64 v[62:63], s[86:87], 0, v[2:3]
	v_or_b32_e32 v2, 0x140, v188
	v_lshlrev_b32_e32 v4, 4, v2
	v_lshl_add_u64 v[64:65], s[86:87], 0, v[4:5]
	v_or_b32_e32 v4, 0x180, v188
	v_lshlrev_b32_e32 v6, 4, v4
	v_lshl_add_u64 v[66:67], s[86:87], 0, v[6:7]
	v_or_b32_e32 v6, 0x1c0, v188
	v_lshlrev_b32_e32 v8, 4, v6
	v_lshl_add_u64 v[68:69], s[86:87], 0, v[8:9]
	v_lshl_add_u64 v[8:9], s[2:3], 0, v[56:57]
	s_mov_b64 s[2:3], 0x1000
	s_ashr_i32 s5, s4, 31
	v_lshl_add_u64 v[58:59], s[88:89], 0, v[56:57]
	v_lshl_add_u64 v[60:61], s[86:87], 0, v[56:57]
	v_lshl_add_u64 v[70:71], v[8:9], 0, s[2:3]
	s_lshl_b64 s[6:7], s[4:5], 13
	s_movk_i32 s5, 0x1000
	v_mov_b32_e32 v57, 0x358637bd
	s_mov_b32 s11, 0xf800000
	v_mov_b32_e32 v79, 0x260
	v_lshlrev_b32_e32 v80, 4, v188
	v_lshlrev_b32_e32 v81, 4, v0
	v_lshlrev_b32_e32 v82, 4, v2
	v_lshlrev_b32_e32 v83, 4, v4
	v_lshlrev_b32_e32 v84, 4, v6
	v_readlane_b32 s12, v254, 40
	global_load_dwordx4 v[140:143], v[60:61], off offset:1024
	global_load_dwordx4 v[144:147], v[60:61], off offset:2048
	global_load_dwordx4 v[148:151], v[60:61], off offset:3072
	global_load_dwordx4 v[152:155], v[62:63], off
	global_load_dwordx4 v[156:159], v[64:65], off
	global_load_dwordx4 v[160:163], v[66:67], off
	global_load_dwordx4 v[164:167], v[68:69], off
.LBB0_793:
	global_load_dwordx4 v[28:31], v[70:71], off offset:-4096
	global_load_dwordx4 v[24:27], v[70:71], off offset:-3072
	global_load_dwordx4 v[20:23], v[70:71], off offset:-2048
	global_load_dwordx4 v[12:15], v[70:71], off
	global_load_dwordx4 v[16:19], v[70:71], off offset:-1024
	global_load_dwordx4 v[8:11], v[70:71], off offset:1024
	global_load_dwordx4 v[0:3], v[70:71], off offset:3072
	global_load_dwordx4 v[4:7], v[70:71], off offset:2048
	s_ashr_i32 s1, s0, 31
	s_lshl_b64 s[0:1], s[0:1], 13
	v_lshl_add_u64 v[32:33], v[58:59], 0, s[0:1]
	global_load_dwordx4 v[86:89], v[60:61], off
	global_load_dwordx4 v[90:93], v[32:33], off
	global_load_dwordx4 v[94:97], v[32:33], off offset:1024
	global_load_dwordx4 v[52:55], v[32:33], off offset:2048
	global_load_dwordx4 v[48:51], v[32:33], off offset:3072
	v_add_co_u32_e32 v98, vcc, s5, v32
	s_add_u32 s8, s88, s0
	s_nop 0
	v_addc_co_u32_e32 v99, vcc, 0, v33, vcc
	global_load_dwordx4 v[44:47], v[98:99], off
	global_load_dwordx4 v[40:43], v[98:99], off offset:1024
	global_load_dwordx4 v[32:35], v[98:99], off offset:3072
	global_load_dwordx4 v[36:39], v[98:99], off offset:2048
	s_addc_u32 s9, s89, s1
	s_add_i32 s68, s68, s4
	s_add_i32 s12, s12, s4
	s_waitcnt vmcnt(16)
	v_mov_b32_e32 v100, v29
	s_waitcnt vmcnt(15)
	v_mov_b32_e32 v101, v25
	v_mov_b32_e32 v104, v31
	v_mov_b32_e32 v105, v27
	v_mov_b32_e32 v98, v28
	v_mov_b32_e32 v99, v24
	v_mov_b32_e32 v102, v30
	v_mov_b32_e32 v103, v26
	s_waitcnt vmcnt(14)
	v_pk_mul_f32 v[106:107], v[22:23], v[22:23]
	v_pk_mul_f32 v[108:109], v[20:21], v[20:21]
	v_pk_mul_f32 v[100:101], v[100:101], v[100:101]
	v_pk_mul_f32 v[104:105], v[104:105], v[104:105]
	s_waitcnt vmcnt(12)
	v_mul_f32_e32 v110, v17, v17
	v_mul_f32_e32 v112, v19, v19
	s_waitcnt vmcnt(11)
	v_pk_mul_f32 v[114:115], v[10:11], v[10:11]
	v_pk_mul_f32 v[116:117], v[8:9], v[8:9]
	v_pk_mov_b32 v[122:123], v[108:109], v[106:107] op_sel:[1,0]
	v_mov_b32_e32 v109, v107
	v_pk_fma_f32 v[98:99], v[98:99], v[98:99], v[100:101]
	v_pk_fma_f32 v[100:101], v[102:103], v[102:103], v[104:105]
	v_mul_f32_e32 v121, v14, v14
	s_waitcnt vmcnt(9)
	v_mul_f32_e32 v118, v5, v5
	v_mul_f32_e32 v120, v7, v7
	v_pk_fma_f32 v[106:107], v[16:17], v[16:17], v[110:111] op_sel_hi:[1,1,0]
	v_pk_fma_f32 v[110:111], v[18:19], v[18:19], v[112:113] op_sel_hi:[1,1,0]
	v_pk_mov_b32 v[112:113], v[116:117], v[114:115] op_sel:[1,0]
	v_mov_b32_e32 v117, v115
	v_pk_add_f32 v[102:103], v[122:123], v[108:109]
	v_pk_add_f32 v[98:99], v[98:99], v[100:101]
	v_mul_f32_e32 v85, v12, v12
	v_mul_f32_e32 v125, v13, v13
	v_mul_f32_e32 v124, v15, v15
	v_mul_f32_e32 v126, v2, v2
	v_mul_f32_e32 v127, v3, v3
	v_pk_fma_f32 v[114:115], v[4:5], v[4:5], v[118:119] op_sel_hi:[1,1,0]
	v_pk_fma_f32 v[118:119], v[6:7], v[6:7], v[120:121] op_sel_hi:[1,1,0]
	v_pk_add_f32 v[104:105], v[112:113], v[116:117]
	s_waitcnt vmcnt(7)
; __device__ __forceinline__ float wave_sum(float v) {
; #pragma unroll
;     for (int o = 1; o < 64; o <<= 1) v += __shfl_xor(v, o);
;     return v;
; }
; template <bool OUT_BF16> __device__ __forceinline__ void rms_rows(const float* X, const float* gain, void* out, int gw, int ngw, int lane) {
;     ...
;         for (int j = 0; j < 8; ++j) { s0 += (v0[j].x * v0[j].x + v0[j].y * v0[j].y) + (v0[j].z * v0[j].z + v0[j].w * v0[j].w); s1 += (v1[j].x * v1[j].x + v1[j].y * v1[j].y) + (v1[j].z * v1[j].z + v1[j].w * v1[j].w); }
;         const float rs0 = 1.0f / sqrtf(wave_sum(s0) * (1.0f / D) + EPS), rs1 = 1.0f / sqrtf(wave_sum(s1) * (1.0f / D) + EPS);
	v_mov_b32_e32 v108, v91
	s_waitcnt vmcnt(6)
	v_mov_b32_e32 v109, v95
	v_mov_b32_e32 v116, v93
	v_mov_b32_e32 v117, v97
	v_pk_add_f32 v[102:103], v[102:103], v[102:103] op_sel:[0,1] op_sel_hi:[1,0]
	v_pk_add_f32 v[98:99], v[98:99], v[98:99] op_sel:[0,1] op_sel_hi:[1,0]
	v_mov_b32_e32 v107, v121
	v_mov_b32_e32 v111, v124
	v_mov_b32_e32 v115, v126
	v_mov_b32_e32 v119, v127
	v_mov_b32_e32 v100, v90
	v_mov_b32_e32 v101, v94
	v_mov_b32_e32 v112, v92
	v_mov_b32_e32 v113, v96
	s_waitcnt vmcnt(5)
	v_pk_mul_f32 v[120:121], v[54:55], v[54:55]
	v_pk_mul_f32 v[122:123], v[52:53], v[52:53]
	v_pk_mul_f32 v[108:109], v[108:109], v[108:109]
	v_pk_mul_f32 v[116:117], v[116:117], v[116:117]
	v_mov_b32_e32 v103, v125
	v_mov_b32_e32 v99, v85
	v_pk_add_f32 v[106:107], v[106:107], v[110:111]
	v_pk_add_f32 v[114:115], v[114:115], v[118:119]
	v_pk_mov_b32 v[118:119], v[122:123], v[120:121] op_sel:[1,0]
	v_mov_b32_e32 v123, v121
	v_pk_fma_f32 v[100:101], v[100:101], v[100:101], v[108:109]
	v_pk_fma_f32 v[108:109], v[112:113], v[112:113], v[116:117]
	v_pk_add_f32 v[98:99], v[98:99], v[102:103]
	s_waitcnt vmcnt(4)
	v_mul_f32_e32 v110, v49, v49
	v_mul_f32_e32 v124, v51, v51
	v_pk_add_f32 v[112:113], v[118:119], v[122:123]
	v_pk_add_f32 v[100:101], v[100:101], v[108:109]
	v_pk_add_f32 v[98:99], v[98:99], v[106:107]
	v_mul_f32_e32 v129, v0, v0
	v_mul_f32_e32 v128, v1, v1
	v_pk_add_f32 v[104:105], v[104:105], v[104:105] op_sel:[0,1] op_sel_hi:[1,0]
	s_waitcnt vmcnt(3)
	v_mul_f32_e32 v131, v44, v44
	v_mul_f32_e32 v132, v45, v45
	v_mul_f32_e32 v133, v46, v46
	v_mul_f32_e32 v134, v47, v47
	v_pk_fma_f32 v[110:111], v[48:49], v[48:49], v[110:111] op_sel_hi:[1,1,0]
	v_pk_fma_f32 v[120:121], v[50:51], v[50:51], v[124:125] op_sel_hi:[1,1,0]
	v_pk_add_f32 v[102:103], v[112:113], v[112:113] op_sel:[0,1] op_sel_hi:[1,0]
	v_pk_add_f32 v[100:101], v[100:101], v[100:101] op_sel:[0,1] op_sel_hi:[1,0]
	v_pk_add_f32 v[98:99], v[98:99], v[98:99] op_sel:[0,1] op_sel_hi:[1,0]
	s_waitcnt vmcnt(2)
	v_pk_mul_f32 v[124:125], v[42:43], v[42:43]
	v_pk_mul_f32 v[126:127], v[40:41], v[40:41]
	v_mov_b32_e32 v105, v128
	v_mov_b32_e32 v111, v133
	v_mov_b32_e32 v121, v134
	v_mov_b32_e32 v103, v132
	v_mov_b32_e32 v101, v131
	v_mov_b32_e32 v99, v129
	v_pk_mov_b32 v[116:117], v[126:127], v[124:125] op_sel:[1,0]
	v_mov_b32_e32 v127, v125
	v_pk_add_f32 v[108:109], v[110:111], v[120:121]
	v_pk_add_f32 v[100:101], v[100:101], v[102:103]
	v_pk_add_f32 v[98:99], v[98:99], v[104:105]
	s_waitcnt vmcnt(0)
	v_mul_f32_e32 v128, v37, v37
	v_mul_f32_e32 v130, v39, v39
	v_pk_add_f32 v[110:111], v[116:117], v[126:127]
	v_pk_add_f32 v[100:101], v[100:101], v[108:109]
	v_pk_add_f32 v[98:99], v[98:99], v[114:115]
	v_mul_f32_e32 v135, v32, v32
	v_mul_f32_e32 v136, v33, v33
	v_mul_f32_e32 v137, v34, v34
	s_waitcnt lgkmcnt(13)
	v_mul_f32_e32 v138, v35, v35
	v_pk_fma_f32 v[118:119], v[36:37], v[36:37], v[128:129] op_sel_hi:[1,1,0]
	v_pk_fma_f32 v[122:123], v[38:39], v[38:39], v[130:131] op_sel_hi:[1,1,0]
	v_pk_add_f32 v[106:107], v[110:111], v[110:111] op_sel:[0,1] op_sel_hi:[1,0]
	v_pk_add_f32 v[100:101], v[100:101], v[100:101] op_sel:[0,1] op_sel_hi:[1,0]
	v_add_f32_e32 v85, v98, v99
	v_mov_b32_e32 v119, v137
	v_mov_b32_e32 v123, v138
	v_mov_b32_e32 v107, v136
	v_mov_b32_e32 v101, v135
	ds_bpermute_b32 v102, v73, v85
	v_pk_add_f32 v[110:111], v[118:119], v[122:123]
	v_pk_add_f32 v[98:99], v[100:101], v[106:107]
	s_waitcnt lgkmcnt(0)
	v_add_f32_e32 v85, v85, v102
	v_pk_add_f32 v[98:99], v[98:99], v[110:111]
	ds_bpermute_b32 v100, v74, v85
	v_add_f32_e32 v98, v98, v99
	ds_bpermute_b32 v99, v73, v98
	s_waitcnt lgkmcnt(1)
	v_add_f32_e32 v85, v85, v100
	ds_bpermute_b32 v100, v75, v85
	s_waitcnt lgkmcnt(1)
	v_add_f32_e32 v98, v98, v99
	ds_bpermute_b32 v99, v74, v98
	s_waitcnt lgkmcnt(1)
	v_add_f32_e32 v85, v85, v100
	ds_bpermute_b32 v100, v76, v85
	s_waitcnt lgkmcnt(1)
	v_add_f32_e32 v98, v98, v99
	ds_bpermute_b32 v99, v75, v98
	s_waitcnt lgkmcnt(1)
	v_add_f32_e32 v85, v85, v100
	ds_bpermute_b32 v100, v77, v85
	s_waitcnt lgkmcnt(1)
	v_add_f32_e32 v98, v98, v99
	ds_bpermute_b32 v99, v76, v98
	s_waitcnt lgkmcnt(1)
	v_add_f32_e32 v85, v85, v100
	ds_bpermute_b32 v100, v78, v85
	s_waitcnt lgkmcnt(1)
	v_add_f32_e32 v98, v98, v99
	ds_bpermute_b32 v99, v77, v98
	s_waitcnt lgkmcnt(1)
	v_add_f32_e32 v85, v85, v100
	v_fmamk_f32 v85, v85, 0x3a000000, v57
	s_waitcnt lgkmcnt(0)
	v_add_f32_e32 v98, v98, v99
	ds_bpermute_b32 v99, v78, v98
	v_mul_f32_e32 v100, 0x4f800000, v85
	v_cmp_gt_f32_e32 vcc, s11, v85
	s_waitcnt lgkmcnt(0)
; __device__ __forceinline__ unsigned pk2(float lo, float hi) { typedef float f2_t __attribute__((ext_vector_type(2))); typedef __bf16 b2_t __attribute__((ext_vector_type(2))); const f2_t v = {lo, hi}; return __builtin_bit_cast(unsigned, __builtin_convertvector(v, b2_t)); }
; template <bool OUT_BF16> __device__ __forceinline__ void rms_rows(const float* X, const float* gain, void* out, int gw, int ngw, int lane) {
;     ...
;         const float rs0 = 1.0f / sqrtf(wave_sum(s0) * (1.0f / D) + EPS), rs1 = 1.0f / sqrtf(wave_sum(s1) * (1.0f / D) + EPS);
; #pragma unroll
;         for (int j = 0; j < 8; ++j) {
;             const f32x4 g = ((const f32x4*)gain)[lane + 64 * j]; const f32x4 o0 = v0[j] * rs0 * g, o1 = v1[j] * rs1 * g;
;             if (OUT_BF16) { v2u w0, w1; w0.x = pk2(o0.x, o0.y); w0.y = pk2(o0.z, o0.w); w1.x = pk2(o1.x, o1.y); w1.y = pk2(o1.z, o1.w);
;                 ((v2u*)((bf16*)out + (size_t)m * D))[lane + 64 * j] = w0; ((v2u*)((bf16*)out + (size_t)(m + ngw) * D))[lane + 64 * j] = w1; }
;             else { ((f32x4*)((float*)out + (size_t)m * D))[lane + 64 * j] = o0; ((f32x4*)((float*)out + (size_t)(m + ngw) * D))[lane + 64 * j] = o1; }
;         }
	v_add_f32_e32 v98, v98, v99
	v_cndmask_b32_e32 v85, v85, v100, vcc
	v_sqrt_f32_e32 v99, v85
	v_fmamk_f32 v98, v98, 0x3a000000, v57
	v_mul_f32_e32 v100, 0x4f800000, v98
	v_cmp_gt_f32_e64 s[0:1], s11, v98
	v_add_u32_e32 v101, -1, v99
	v_add_u32_e32 v102, 1, v99
	v_cndmask_b32_e64 v98, v98, v100, s[0:1]
	v_sqrt_f32_e32 v100, v98
	v_fma_f32 v103, -v101, v99, v85
	v_fma_f32 v104, -v102, v99, v85
	v_cmp_ge_f32_e64 s[2:3], 0, v103
	s_nop 1
	v_cndmask_b32_e64 v99, v99, v101, s[2:3]
	v_cmp_lt_f32_e64 s[2:3], 0, v104
	v_add_u32_e32 v101, -1, v100
	v_fma_f32 v104, -v101, v100, v98
	v_cndmask_b32_e64 v99, v99, v102, s[2:3]
	v_add_u32_e32 v102, 1, v100
	v_mul_f32_e32 v103, 0x37800000, v99
	v_fma_f32 v105, -v102, v100, v98
	v_cndmask_b32_e32 v99, v99, v103, vcc
	v_cmp_ge_f32_e32 vcc, 0, v104
	v_cmp_class_f32_e64 s[2:3], v85, v79
	s_nop 0
	v_cndmask_b32_e32 v100, v100, v101, vcc
	v_cmp_lt_f32_e32 vcc, 0, v105
	v_cndmask_b32_e64 v85, v99, v85, s[2:3]
	s_nop 0
	v_cndmask_b32_e32 v99, v100, v102, vcc
	v_div_scale_f32 v100, s[2:3], v85, v85, 1.0
	v_mul_f32_e32 v102, 0x37800000, v99
	v_rcp_f32_e32 v103, v100
	v_cndmask_b32_e64 v99, v99, v102, s[0:1]
	v_cmp_class_f32_e64 s[0:1], v98, v79
	v_div_scale_f32 v101, vcc, 1.0, v85, 1.0
	s_nop 0
	v_cndmask_b32_e64 v99, v99, v98, s[0:1]
	v_div_scale_f32 v102, s[0:1], v99, v99, 1.0
	v_rcp_f32_e32 v105, v102
	v_fma_f32 v98, -v100, v103, 1.0
	v_fmac_f32_e32 v103, v98, v103
	v_mul_f32_e32 v98, v101, v103
	v_fma_f32 v106, -v100, v98, v101
	v_fma_f32 v107, -v102, v105, 1.0
	v_div_scale_f32 v104, s[0:1], 1.0, v99, 1.0
	v_fmac_f32_e32 v98, v106, v103
	v_fmac_f32_e32 v105, v107, v105
	v_fma_f32 v100, -v100, v98, v101
	v_mul_f32_e32 v101, v104, v105
	v_div_fmas_f32 v98, v100, v103, v98
	v_fma_f32 v100, -v102, v101, v104
	v_fmac_f32_e32 v101, v100, v105
	v_div_fixup_f32 v98, v98, v85, 1.0
	v_fma_f32 v85, -v102, v101, v104
	s_mov_b64 vcc, s[0:1]
	v_pk_mul_f32 v[28:29], v[28:29], v[98:99] op_sel_hi:[1,0]
	v_pk_mul_f32 v[30:31], v[30:31], v[98:99] op_sel_hi:[1,0]
	v_div_fmas_f32 v85, v85, v105, v101
	v_pk_mul_f32 v[30:31], v[88:89], v[30:31]
	v_pk_mul_f32 v[28:29], v[86:87], v[28:29]
	v_div_fixup_f32 v100, v85, v99, 1.0
	global_store_dwordx4 v[70:71], v[28:31], off offset:-4096
	v_pk_mul_f32 v[26:27], v[26:27], v[98:99] op_sel_hi:[1,0]
	v_pk_mul_f32 v[24:25], v[24:25], v[98:99] op_sel_hi:[1,0]
	v_pk_mul_f32 v[28:29], v[90:91], v[100:101] op_sel_hi:[1,0]
	v_pk_mul_f32 v[30:31], v[92:93], v[100:101] op_sel_hi:[1,0]
	v_pk_mul_f32 v[28:29], v[86:87], v[28:29]
	v_pk_mul_f32 v[30:31], v[88:89], v[30:31]
	global_store_dwordx4 v80, v[28:31], s[8:9]
	s_nop 0
	v_pk_mul_f32 v[86:87], v[96:97], v[100:101] op_sel_hi:[1,0]
	v_pk_mul_f32 v[88:89], v[94:95], v[100:101] op_sel_hi:[1,0]
	v_pk_mul_f32 v[22:23], v[22:23], v[98:99] op_sel_hi:[1,0]
	v_pk_mul_f32 v[20:21], v[20:21], v[98:99] op_sel_hi:[1,0]
	v_pk_mul_f32 v[18:19], v[18:19], v[98:99] op_sel_hi:[1,0]
	v_pk_mul_f32 v[16:17], v[16:17], v[98:99] op_sel_hi:[1,0]
	v_pk_mul_f32 v[14:15], v[14:15], v[98:99] op_sel_hi:[1,0]
	v_pk_mul_f32 v[12:13], v[12:13], v[98:99] op_sel_hi:[1,0]
	v_pk_mul_f32 v[10:11], v[10:11], v[98:99] op_sel_hi:[1,0]
	v_pk_mul_f32 v[8:9], v[8:9], v[98:99] op_sel_hi:[1,0]
	v_pk_mul_f32 v[6:7], v[6:7], v[98:99] op_sel_hi:[1,0]
	v_pk_mul_f32 v[4:5], v[4:5], v[98:99] op_sel_hi:[1,0]
	v_pk_mul_f32 v[2:3], v[2:3], v[98:99] op_sel_hi:[1,0]
	v_pk_mul_f32 v[0:1], v[0:1], v[98:99] op_sel_hi:[1,0]
	s_add_i32 s0, s68, s14
	s_add_i32 s1, s10, s12
	s_cmp_gt_i32 s1, s97
	s_nop 0
	v_pk_mul_f32 v[24:25], v[140:141], v[24:25]
	v_pk_mul_f32 v[26:27], v[142:143], v[26:27]
	v_pk_mul_f32 v[28:29], v[140:141], v[88:89]
	v_pk_mul_f32 v[30:31], v[142:143], v[86:87]
	global_store_dwordx4 v[70:71], v[24:27], off offset:-3072
	global_store_dwordx4 v80, v[28:31], s[8:9] offset:1024
	s_nop 0
	s_nop 0
	v_pk_mul_f32 v[20:21], v[20:21], v[144:145]
	v_pk_mul_f32 v[28:29], v[54:55], v[100:101] op_sel_hi:[1,0]
	v_pk_mul_f32 v[30:31], v[52:53], v[100:101] op_sel_hi:[1,0]
	v_pk_mul_f32 v[22:23], v[22:23], v[146:147]
	v_pk_mul_f32 v[24:25], v[144:145], v[30:31]
	v_pk_mul_f32 v[26:27], v[146:147], v[28:29]
	global_store_dwordx4 v[70:71], v[20:23], off offset:-2048
	global_store_dwordx4 v80, v[24:27], s[8:9] offset:2048
	s_nop 0
	s_nop 0
	v_pk_mul_f32 v[16:17], v[16:17], v[148:149]
	v_pk_mul_f32 v[24:25], v[50:51], v[100:101] op_sel_hi:[1,0]
	v_pk_mul_f32 v[26:27], v[48:49], v[100:101] op_sel_hi:[1,0]
	v_pk_mul_f32 v[18:19], v[18:19], v[150:151]
	v_pk_mul_f32 v[20:21], v[26:27], v[148:149]
	v_pk_mul_f32 v[22:23], v[24:25], v[150:151]
	global_store_dwordx4 v[70:71], v[16:19], off offset:-1024
	global_store_dwordx4 v80, v[20:23], s[8:9] offset:3072
	s_nop 0
	s_nop 0
	v_pk_mul_f32 v[12:13], v[12:13], v[152:153]
	v_pk_mul_f32 v[20:21], v[46:47], v[100:101] op_sel_hi:[1,0]
	v_pk_mul_f32 v[22:23], v[44:45], v[100:101] op_sel_hi:[1,0]
	v_pk_mul_f32 v[14:15], v[14:15], v[154:155]
	v_pk_mul_f32 v[16:17], v[22:23], v[152:153]
	v_pk_mul_f32 v[18:19], v[20:21], v[154:155]
	global_store_dwordx4 v[70:71], v[12:15], off
	global_store_dwordx4 v81, v[16:19], s[8:9]
	s_nop 0
	s_nop 0
	v_pk_mul_f32 v[8:9], v[8:9], v[156:157]
	v_pk_mul_f32 v[16:17], v[42:43], v[100:101] op_sel_hi:[1,0]
	v_pk_mul_f32 v[18:19], v[40:41], v[100:101] op_sel_hi:[1,0]
	v_pk_mul_f32 v[10:11], v[10:11], v[158:159]
	v_pk_mul_f32 v[12:13], v[18:19], v[156:157]
	v_pk_mul_f32 v[14:15], v[16:17], v[158:159]
	global_store_dwordx4 v[70:71], v[8:11], off offset:1024
	global_store_dwordx4 v82, v[12:15], s[8:9]
	s_nop 0
	s_nop 0
	v_pk_mul_f32 v[4:5], v[4:5], v[160:161]
	v_pk_mul_f32 v[12:13], v[38:39], v[100:101] op_sel_hi:[1,0]
	v_pk_mul_f32 v[14:15], v[36:37], v[100:101] op_sel_hi:[1,0]
	v_pk_mul_f32 v[6:7], v[6:7], v[162:163]
	v_pk_mul_f32 v[8:9], v[14:15], v[160:161]
	v_pk_mul_f32 v[10:11], v[12:13], v[162:163]
	global_store_dwordx4 v[70:71], v[4:7], off offset:2048
	global_store_dwordx4 v83, v[8:11], s[8:9]
	s_nop 0
	s_nop 0
	v_pk_mul_f32 v[0:1], v[0:1], v[164:165]
	v_pk_mul_f32 v[8:9], v[34:35], v[100:101] op_sel_hi:[1,0]
	v_pk_mul_f32 v[10:11], v[32:33], v[100:101] op_sel_hi:[1,0]
	v_pk_mul_f32 v[2:3], v[2:3], v[166:167]
	v_pk_mul_f32 v[4:5], v[10:11], v[164:165]
	v_pk_mul_f32 v[6:7], v[8:9], v[166:167]
	global_store_dwordx4 v[70:71], v[0:3], off offset:3072
	global_store_dwordx4 v84, v[4:7], s[8:9]
	v_lshl_add_u64 v[70:71], v[70:71], 0, s[6:7]
	s_cbranch_scc0 .LBB0_793
	v_readlane_b32 s0, v254, 41
	s_add_i32 s68, s0, s12
; template <bool OUT_BF16> __device__ __forceinline__ void rms_rows(const float* X, const float* gain, void* out, int gw, int ngw, int lane) {
;     ...
;     for (; m < M; m += ngw) {
;         const f32x4* xr = (const f32x4*)(X + (size_t)m * D) + lane;
;         f32x4 v[8]; float s = 0.f;
; #pragma unroll
;         for (int j = 0; j < 8; ++j) { v[j] = xr[64 * j]; s += (v[j].x * v[j].x + v[j].y * v[j].y) + (v[j].z * v[j].z + v[j].w * v[j].w); }
;         const float rs = 1.0f / sqrtf(wave_sum(s) * (1.0f / D) + EPS);
.LBB0_795:
	s_cmp_eq_u32 s0, s0
	s_cbranch_scc1 .LBB0_798
	v_mbcnt_hi_u32_b32 v0, -1, v72
	v_and_b32_e32 v1, 64, v0
	v_add_u32_e32 v1, 64, v1
	v_xor_b32_e32 v2, 1, v0
	v_cmp_lt_i32_e32 vcc, v2, v1
	v_mov_b32_e32 v57, 0
	s_ashr_i32 s69, s68, 31
	v_cndmask_b32_e32 v2, v0, v2, vcc
	v_lshlrev_b32_e32 v24, 2, v2
	v_xor_b32_e32 v2, 2, v0
	v_cmp_lt_i32_e32 vcc, v2, v1
	s_lshl_b64 s[0:1], s[68:69], 13
	s_add_u32 s0, s88, s0
	v_cndmask_b32_e32 v2, v0, v2, vcc
	v_lshlrev_b32_e32 v25, 2, v2
	v_xor_b32_e32 v2, 4, v0
	v_cmp_lt_i32_e32 vcc, v2, v1
	s_addc_u32 s1, s89, s1
	s_ashr_i32 s15, s14, 31
	v_cndmask_b32_e32 v2, v0, v2, vcc
	v_lshlrev_b32_e32 v26, 2, v2
	v_xor_b32_e32 v2, 8, v0
	v_cmp_lt_i32_e32 vcc, v2, v1
	v_lshl_add_u64 v[12:13], s[86:87], 0, v[56:57]
	s_lshl_b64 s[2:3], s[14:15], 13
	v_cndmask_b32_e32 v2, v0, v2, vcc
	v_lshlrev_b32_e32 v27, 2, v2
	v_xor_b32_e32 v2, 16, v0
	v_cmp_lt_i32_e32 vcc, v2, v1
	v_mov_b32_e32 v30, 0x358637bd
	s_mov_b32 s4, 0xf800000
	v_cndmask_b32_e32 v2, v0, v2, vcc
	v_lshlrev_b32_e32 v28, 2, v2
	v_xor_b32_e32 v2, 32, v0
	v_cmp_lt_i32_e32 vcc, v2, v1
	v_mov_b32_e32 v1, v57
	v_mov_b32_e32 v31, 0x260
	v_cndmask_b32_e32 v0, v0, v2, vcc
	v_lshlrev_b32_e32 v29, 2, v0
	v_or_b32_e32 v0, 0x1000, v56
	v_lshl_add_u64 v[14:15], s[86:87], 0, v[0:1]
	v_or_b32_e32 v0, 0x1400, v56
	v_lshl_add_u64 v[16:17], s[86:87], 0, v[0:1]
	v_or_b32_e32 v0, 0x1800, v56
	v_lshl_add_u64 v[18:19], s[86:87], 0, v[0:1]
	v_or_b32_e32 v0, 0x1c00, v56
	v_lshl_add_u64 v[20:21], s[86:87], 0, v[0:1]
	v_lshl_add_u64 v[0:1], s[0:1], 0, v[56:57]
	s_mov_b64 s[0:1], 0x1000
	v_lshl_add_u64 v[22:23], v[0:1], 0, s[0:1]
